# seam poll backoff s_sleep 2 -> 1 in the 21 counter-barrier poll loops, on top of addpart_vm
# speedup vs baseline: 1.0176x; 1.0176x over previous
.LBB0_165:
	global_load_dword v3, v2, s[18:19] sc1
	s_waitcnt vmcnt(0)
	v_readfirstlane_b32 s2, v3
	s_cmp_ge_u32 s2, s75
	s_mov_b64 s[2:3], -1
	s_cbranch_scc1 .LBB0_164
	s_mov_b64 s[2:3], 0
	s_sleep 1
	s_branch .LBB0_164

.LBB0_280:
	global_load_dword v1, v0, s[4:5] sc1
	s_waitcnt vmcnt(0)
	v_readfirstlane_b32 s6, v1
	s_cmp_ge_u32 s6, s75
	s_mov_b64 s[6:7], -1
	s_cbranch_scc1 .LBB0_279
	s_mov_b64 s[6:7], 0
	s_sleep 1
	s_branch .LBB0_279

.LBB0_303:
	global_load_dword v0, v149, s[38:39] offset:1792 sc1
	s_waitcnt vmcnt(0)
	v_readfirstlane_b32 s10, v0
	s_cmp_gt_u32 s10, 7
	s_mov_b64 s[10:11], -1
	s_cbranch_scc1 .LBB0_302
	s_mov_b64 s[10:11], 0
	s_sleep 1
	s_branch .LBB0_302

.LBB0_359:
	global_load_dword v0, v149, s[38:39] offset:1536 sc1
	s_waitcnt vmcnt(0)
	v_readfirstlane_b32 s10, v0
	s_cmp_gt_u32 s10, 63
	s_mov_b64 s[10:11], -1
	s_cbranch_scc1 .LBB0_358
	s_mov_b64 s[10:11], 0
	s_sleep 1
	s_branch .LBB0_358

.LBB0_419:
	global_load_dword v1, v0, s[4:5] sc1
	s_waitcnt vmcnt(0)
	v_readfirstlane_b32 s6, v1
	s_cmp_ge_u32 s6, s8
	s_mov_b64 s[6:7], -1
	s_cbranch_scc1 .LBB0_418
	s_mov_b64 s[6:7], 0
	s_sleep 1
	s_branch .LBB0_418

.LBB0_560:
	global_load_dword v1, v0, s[38:39] offset:256 sc1
	s_waitcnt vmcnt(0)
	v_readfirstlane_b32 s2, v1
	s_cmp_ge_u32 s2, s75
	s_mov_b64 s[2:3], -1
	s_cbranch_scc1 .LBB0_559
	s_mov_b64 s[2:3], 0
	s_sleep 1
	s_branch .LBB0_559

.LBB0_587:
	global_load_dword v129, v128, s[20:21] sc1
	s_waitcnt vmcnt(0)
	v_readfirstlane_b32 s22, v129
	s_cmp_gt_u32 s22, 2
	s_mov_b64 s[22:23], -1
	s_cbranch_scc1 .LBB0_586
	s_mov_b64 s[22:23], 0
	s_sleep 1
	s_branch .LBB0_586

.LBB0_638:
	global_load_dword v1, v0, s[4:5] sc1
	s_waitcnt vmcnt(0)
	v_readfirstlane_b32 s6, v1
	s_cmp_ge_u32 s6, s10
	s_mov_b64 s[6:7], -1
	s_cbranch_scc1 .LBB0_637
	s_mov_b64 s[6:7], 0
	s_sleep 1
	s_branch .LBB0_637

.LBB0_915:
	global_load_dword v1, v0, s[4:5] sc1
	s_waitcnt vmcnt(0)
	v_readfirstlane_b32 s6, v1
	s_cmp_ge_u32 s6, s85
	s_mov_b64 s[6:7], -1
	s_cbranch_scc1 .LBB0_914
	s_mov_b64 s[6:7], 0
	s_sleep 1
	s_branch .LBB0_914

.LBB0_944:
	global_load_dword v0, v1, s[38:39] offset:1024 sc1
	s_waitcnt vmcnt(0)
	v_readfirstlane_b32 s4, v0
	s_cmp_gt_u32 s4, 7
	s_mov_b64 s[4:5], -1
	s_cbranch_scc1 .LBB0_943
	s_mov_b64 s[4:5], 0
	s_sleep 1
	s_branch .LBB0_943

.LBB0_999:
	global_load_dword v0, v1, s[38:39] offset:768 sc1
	s_waitcnt vmcnt(0)
	v_readfirstlane_b32 s4, v0
	s_cmpk_gt_u32 s4, 0xff
	s_mov_b64 s[4:5], -1
	s_cbranch_scc1 .LBB0_998
	s_mov_b64 s[4:5], 0
	s_sleep 1
	s_branch .LBB0_998

.LBB0_1281:
	global_load_dword v1, v0, s[38:39] offset:512 sc1
	s_waitcnt vmcnt(0)
	v_readfirstlane_b32 s0, v1
	s_cmp_ge_u32 s0, s75
	s_mov_b64 s[0:1], -1
	s_cbranch_scc1 .LBB0_1280
	s_mov_b64 s[0:1], 0
	s_sleep 1
	s_branch .LBB0_1280

.LBB0_1343:
	global_load_dword v1, v0, s[2:3] sc1
	s_waitcnt vmcnt(0)
	v_readfirstlane_b32 s4, v1
	s_cmp_ge_u32 s4, s6
	s_mov_b64 s[4:5], -1
	s_cbranch_scc1 .LBB0_1342
	s_mov_b64 s[4:5], 0
	s_sleep 1
	s_branch .LBB0_1342
